# RWKV: cumulative-decay stage with immediate LDS offsets per direction; substitution stage accumulates into the pre-scaled W register, waits merged per two steps
# speedup vs baseline: 1.0302x; 1.0048x over previous
; __device__ __forceinline__ void rwkv_chain(LAS unsigned char* lds, int cid, const bf16_t* P0, const float* mu, const float* w0, const float* w2, const float* a0, const float* a2, ...
;     ...
;         { RW_IDS if (tid < 64) { float lw[32];
; #pragma unroll
;             for (int s = 0; s < 32; ++s) lw[s] = wS[(dir ? 31 - s : s) * 64 + tid];
; #pragma unroll
;             for (int s = 1; s < 32; ++s) lw[s] += lw[s - 1];
; #pragma unroll
;             for (int s = 0; s < 32; ++s) wS[(dir ? 31 - s : s) * 64 + tid] = lw[s]; } }
.LBB0_514:
	s_or_b64 exec, exec, s[12:13]
	v_mov_b32_e32 v8, v200
	s_waitcnt lgkmcnt(0)
	s_barrier
	s_nop 0
	v_cmp_gt_i32_e32 vcc, 64, v8
	s_and_saveexec_b64 s[12:13], vcc
	s_cbranch_execz .LBB0_516
	v_lshl_add_u32 v8, v8, 2, 0
	s_and_b64 vcc, exec, s[10:11]
	s_cbranch_vccnz .Lrw_cum_rev
	ds_read_b32 v9, v8 offset:24576
	ds_read_b32 v17, v8 offset:24832
	ds_read_b32 v18, v8 offset:25088
	ds_read_b32 v19, v8 offset:25344
	ds_read_b32 v20, v8 offset:25600
	ds_read_b32 v21, v8 offset:25856
	ds_read_b32 v22, v8 offset:26112
	ds_read_b32 v23, v8 offset:26368
	ds_read_b32 v32, v8 offset:26624
	ds_read_b32 v33, v8 offset:26880
	ds_read_b32 v34, v8 offset:27136
	ds_read_b32 v35, v8 offset:27392
	ds_read_b32 v39, v8 offset:27648
	ds_read_b32 v114, v8 offset:27904
	ds_read_b32 v115, v8 offset:28160
	ds_read_b32 v116, v8 offset:28416
	ds_read_b32 v125, v8 offset:28672
	ds_read_b32 v126, v8 offset:28928
	ds_read_b32 v127, v8 offset:29184
	ds_read_b32 v128, v8 offset:29440
	ds_read_b32 v129, v8 offset:29696
	ds_read_b32 v130, v8 offset:29952
	ds_read_b32 v131, v8 offset:30208
	ds_read_b32 v132, v8 offset:30464
	ds_read_b32 v140, v8 offset:30720
	ds_read_b32 v141, v8 offset:30976
	ds_read_b32 v142, v8 offset:31232
	ds_read_b32 v143, v8 offset:31488
	ds_read_b32 v144, v8 offset:31744
	ds_read_b32 v145, v8 offset:32000
	ds_read_b32 v146, v8 offset:32256
	ds_read_b32 v147, v8 offset:32512
	s_waitcnt lgkmcnt(15)
	v_add_f32_e32 v17, v9, v17
	v_add_f32_e32 v18, v17, v18
	v_add_f32_e32 v19, v18, v19
	v_add_f32_e32 v20, v19, v20
	v_add_f32_e32 v21, v20, v21
	v_add_f32_e32 v22, v21, v22
	v_add_f32_e32 v23, v22, v23
	v_add_f32_e32 v32, v23, v32
	v_add_f32_e32 v33, v32, v33
	v_add_f32_e32 v34, v33, v34
	v_add_f32_e32 v35, v34, v35
	v_add_f32_e32 v39, v35, v39
	v_add_f32_e32 v114, v39, v114
	v_add_f32_e32 v115, v114, v115
	v_add_f32_e32 v116, v115, v116
	v_add_f32_e32 v125, v116, v125
	s_waitcnt lgkmcnt(14)
	v_add_f32_e32 v126, v125, v126
	s_waitcnt lgkmcnt(13)
	v_add_f32_e32 v127, v126, v127
	s_waitcnt lgkmcnt(12)
	v_add_f32_e32 v128, v127, v128
	s_waitcnt lgkmcnt(11)
	v_add_f32_e32 v129, v128, v129
	s_waitcnt lgkmcnt(10)
	v_add_f32_e32 v130, v129, v130
	s_waitcnt lgkmcnt(9)
	v_add_f32_e32 v131, v130, v131
	s_waitcnt lgkmcnt(8)
	v_add_f32_e32 v132, v131, v132
	s_waitcnt lgkmcnt(7)
	v_add_f32_e32 v140, v132, v140
	s_waitcnt lgkmcnt(6)
	v_add_f32_e32 v141, v140, v141
	s_waitcnt lgkmcnt(5)
	v_add_f32_e32 v142, v141, v142
	s_waitcnt lgkmcnt(4)
	v_add_f32_e32 v143, v142, v143
	s_waitcnt lgkmcnt(3)
	v_add_f32_e32 v144, v143, v144
	s_waitcnt lgkmcnt(2)
	v_add_f32_e32 v145, v144, v145
	s_waitcnt lgkmcnt(1)
	v_add_f32_e32 v146, v145, v146
	s_waitcnt lgkmcnt(0)
	v_add_f32_e32 v147, v146, v147
	ds_write_b32 v8, v17 offset:24832
	ds_write_b32 v8, v18 offset:25088
	ds_write_b32 v8, v19 offset:25344
	ds_write_b32 v8, v20 offset:25600
	ds_write_b32 v8, v21 offset:25856
	ds_write_b32 v8, v22 offset:26112
	ds_write_b32 v8, v23 offset:26368
	ds_write_b32 v8, v32 offset:26624
	ds_write_b32 v8, v33 offset:26880
	ds_write_b32 v8, v34 offset:27136
	ds_write_b32 v8, v35 offset:27392
	ds_write_b32 v8, v39 offset:27648
	ds_write_b32 v8, v114 offset:27904
	ds_write_b32 v8, v115 offset:28160
	ds_write_b32 v8, v116 offset:28416
	ds_write_b32 v8, v125 offset:28672
	ds_write_b32 v8, v126 offset:28928
	ds_write_b32 v8, v127 offset:29184
	ds_write_b32 v8, v128 offset:29440
	ds_write_b32 v8, v129 offset:29696
	ds_write_b32 v8, v130 offset:29952
	ds_write_b32 v8, v131 offset:30208
	ds_write_b32 v8, v132 offset:30464
	ds_write_b32 v8, v140 offset:30720
	ds_write_b32 v8, v141 offset:30976
	ds_write_b32 v8, v142 offset:31232
	ds_write_b32 v8, v143 offset:31488
	ds_write_b32 v8, v144 offset:31744
	ds_write_b32 v8, v145 offset:32000
	ds_write_b32 v8, v146 offset:32256
	ds_write_b32 v8, v147 offset:32512
	s_branch .LBB0_516
; __device__ __forceinline__ void rwkv_chain(LAS unsigned char* lds, int cid, const bf16_t* P0, const float* mu, const float* w0, const float* w2, const float* a0, const float* a2, ...
;     ...
;         { RW_IDS if (tid < 64) { float lw[32];
; #pragma unroll
;             for (int s = 0; s < 32; ++s) lw[s] = wS[(dir ? 31 - s : s) * 64 + tid];
; #pragma unroll
;             for (int s = 1; s < 32; ++s) lw[s] += lw[s - 1];
; #pragma unroll
;             for (int s = 0; s < 32; ++s) wS[(dir ? 31 - s : s) * 64 + tid] = lw[s]; } }
.Lrw_cum_rev:
	ds_read_b32 v9, v8 offset:32512
	ds_read_b32 v17, v8 offset:32256
	ds_read_b32 v18, v8 offset:32000
	ds_read_b32 v19, v8 offset:31744
	ds_read_b32 v20, v8 offset:31488
	ds_read_b32 v21, v8 offset:31232
	ds_read_b32 v22, v8 offset:30976
	ds_read_b32 v23, v8 offset:30720
	ds_read_b32 v32, v8 offset:30464
	ds_read_b32 v33, v8 offset:30208
	ds_read_b32 v34, v8 offset:29952
	ds_read_b32 v35, v8 offset:29696
	ds_read_b32 v39, v8 offset:29440
	ds_read_b32 v114, v8 offset:29184
	ds_read_b32 v115, v8 offset:28928
	ds_read_b32 v116, v8 offset:28672
	ds_read_b32 v125, v8 offset:28416
	ds_read_b32 v126, v8 offset:28160
	ds_read_b32 v127, v8 offset:27904
	ds_read_b32 v128, v8 offset:27648
	ds_read_b32 v129, v8 offset:27392
	ds_read_b32 v130, v8 offset:27136
	ds_read_b32 v131, v8 offset:26880
	ds_read_b32 v132, v8 offset:26624
	ds_read_b32 v140, v8 offset:26368
	ds_read_b32 v141, v8 offset:26112
	ds_read_b32 v142, v8 offset:25856
	ds_read_b32 v143, v8 offset:25600
	ds_read_b32 v144, v8 offset:25344
	ds_read_b32 v145, v8 offset:25088
	ds_read_b32 v146, v8 offset:24832
	ds_read_b32 v147, v8 offset:24576
	s_waitcnt lgkmcnt(15)
	v_add_f32_e32 v17, v9, v17
	v_add_f32_e32 v18, v17, v18
	v_add_f32_e32 v19, v18, v19
	v_add_f32_e32 v20, v19, v20
	v_add_f32_e32 v21, v20, v21
	v_add_f32_e32 v22, v21, v22
	v_add_f32_e32 v23, v22, v23
	v_add_f32_e32 v32, v23, v32
	v_add_f32_e32 v33, v32, v33
	v_add_f32_e32 v34, v33, v34
	v_add_f32_e32 v35, v34, v35
	v_add_f32_e32 v39, v35, v39
	v_add_f32_e32 v114, v39, v114
	v_add_f32_e32 v115, v114, v115
	v_add_f32_e32 v116, v115, v116
	v_add_f32_e32 v125, v116, v125
	s_waitcnt lgkmcnt(14)
	v_add_f32_e32 v126, v125, v126
	s_waitcnt lgkmcnt(13)
	v_add_f32_e32 v127, v126, v127
	s_waitcnt lgkmcnt(12)
	v_add_f32_e32 v128, v127, v128
	s_waitcnt lgkmcnt(11)
	v_add_f32_e32 v129, v128, v129
	s_waitcnt lgkmcnt(10)
	v_add_f32_e32 v130, v129, v130
	s_waitcnt lgkmcnt(9)
	v_add_f32_e32 v131, v130, v131
	s_waitcnt lgkmcnt(8)
	v_add_f32_e32 v132, v131, v132
	s_waitcnt lgkmcnt(7)
	v_add_f32_e32 v140, v132, v140
	s_waitcnt lgkmcnt(6)
	v_add_f32_e32 v141, v140, v141
	s_waitcnt lgkmcnt(5)
	v_add_f32_e32 v142, v141, v142
	s_waitcnt lgkmcnt(4)
	v_add_f32_e32 v143, v142, v143
	s_waitcnt lgkmcnt(3)
	v_add_f32_e32 v144, v143, v144
	s_waitcnt lgkmcnt(2)
	v_add_f32_e32 v145, v144, v145
	s_waitcnt lgkmcnt(1)
	v_add_f32_e32 v146, v145, v146
	s_waitcnt lgkmcnt(0)
	v_add_f32_e32 v147, v146, v147
	ds_write_b32 v8, v17 offset:32256
	ds_write_b32 v8, v18 offset:32000
	ds_write_b32 v8, v19 offset:31744
	ds_write_b32 v8, v20 offset:31488
	ds_write_b32 v8, v21 offset:31232
	ds_write_b32 v8, v22 offset:30976
	ds_write_b32 v8, v23 offset:30720
	ds_write_b32 v8, v32 offset:30464
	ds_write_b32 v8, v33 offset:30208
	ds_write_b32 v8, v34 offset:29952
	ds_write_b32 v8, v35 offset:29696
	ds_write_b32 v8, v39 offset:29440
	ds_write_b32 v8, v114 offset:29184
	ds_write_b32 v8, v115 offset:28928
	ds_write_b32 v8, v116 offset:28672
	ds_write_b32 v8, v125 offset:28416
	ds_write_b32 v8, v126 offset:28160
	ds_write_b32 v8, v127 offset:27904
	ds_write_b32 v8, v128 offset:27648
	ds_write_b32 v8, v129 offset:27392
	ds_write_b32 v8, v130 offset:27136
	ds_write_b32 v8, v131 offset:26880
	ds_write_b32 v8, v132 offset:26624
	ds_write_b32 v8, v140 offset:26368
	ds_write_b32 v8, v141 offset:26112
	ds_write_b32 v8, v142 offset:25856
	ds_write_b32 v8, v143 offset:25600
	ds_write_b32 v8, v144 offset:25344
	ds_write_b32 v8, v145 offset:25088
	ds_write_b32 v8, v146 offset:24832
	ds_write_b32 v8, v147 offset:24576

; #define LAS __attribute__((address_space(3)))
; template <int CTRL> __device__ __forceinline__ float dppf(float x) { return __builtin_bit_cast(float, __builtin_amdgcn_mov_dpp(__builtin_bit_cast(int, x), CTRL, 0xf, 0xf, true)); }
; __device__ __forceinline__ f32x4 mfma16(bf16x8 bfrag, bf16x8 afrag, f32x4 acc) { return __builtin_amdgcn_mfma_f32_16x16x32_bf16(bfrag, afrag, acc, 0, 0, 0); }
; __device__ __forceinline__ void rwkv_chain(LAS unsigned char* lds, int cid, const bf16_t* P0, const float* mu, const float* w0, const float* w2, const float* a0, const float* a2, ...
;     ...
;         f32x4 oacc = (f32x4){0.f, 0.f, 0.f, 0.f};
;         { RW_IDS f32x4 wacc = (f32x4){0.f, 0.f, 0.f, 0.f};
; #pragma unroll
;           for (int ks = 0; ks < 2; ++ks) { const bf16x8 sf = ldsfrag(S0b, 72, vt * 16, ks * 32, fr, fq);
;               wacc = mfma16(ldsfrag(At, 72, tt2 * 16, ks * 32, fr, fq), sf, wacc); oacc = mfma16(ldsfrag(Rt, 72, tt2 * 16, ks * 32, fr, fq), sf, oacc); }
;           const bf16x8 vf = ldsfrag(VT, 40, vt * 16, 0, fr, fq);
;           wacc = mfma16(ldsfrag(NakT, 40, tt2 * 16, 0, fr, fq), vf, wacc); oacc = mfma16(ldsfrag(MkrT, 40, tt2 * 16, 0, fr, fq), vf, oacc);
; #pragma unroll
;           for (int n2 = 0; n2 < 2; ++n2) st[n2] = mfma16(ldsfrag(KtT, 40, (tt2 * 2 + n2) * 16, 0, fr, fq), vf, st[n2]);
; #pragma unroll
;           for (int e = 0; e < 4; ++e) WS[(tt2 * 16 + fq * 4 + e) * 64 + vt * 16 + fr] = wacc[e]; }
;         __syncthreads();
;         { RW_IDS if (wid < 4) { const int v = wid * 16 + (lane >> 2), p = lane & 3; const LAS float* NTp = NT4 + p * 384; float u[8];
; #pragma unroll
;             for (int j = 0; j < 8; ++j) u[j] = 0.f;
; #pragma unroll
;             for (int t = 0; t < 32; ++t) { float q0 = (p == 0) ? WS[t * 64 + v] : 0.f, q1 = 0.f;
; #pragma unroll
;                 for (int j4 = 0; j4 < ((t + 3) / 4 + 3) / 4; ++j4) { const f32x4 nv = *(const LAS f32x4*)(NTp + t * 12 + j4 * 4);
;                     q0 += u[j4 * 4] * nv[0]; q1 += u[j4 * 4 + 1] * nv[1]; q0 += u[j4 * 4 + 2] * nv[2]; q1 += u[j4 * 4 + 3] * nv[3]; }
;                 float q = q0 + q1; q += dppf<0xB1>(q); q += dppf<0x4E>(q);
;                 u[t >> 2] = ((t & 3) == p) ? q : u[t >> 2]; asm volatile("" ::: "memory"); }
.LBB0_534:
	v_mov_b32_e32 v8, v200
	s_waitcnt lgkmcnt(0)
	s_barrier
	s_add_i32 s14, 0, 0x1d800
	v_readfirstlane_b32 s7, v8
	s_bfe_u32 s12, s7, 0x10006
	s_ashr_i32 s7, s7, 3
	v_and_b32_e32 v39, 15, v8
	v_bfe_u32 v118, v8, 4, 2
	v_bfi_b32 v8, -16, s7, v8
	v_mul_lo_u32 v28, v8, s76
	v_mul_lo_u32 v13, v8, s83
	v_lshl_or_b32 v8, s12, 5, v39
	v_lshlrev_b32_e32 v114, 4, v118
	v_lshl_or_b32 v12, s12, 4, v39
	v_mul_u32_u24_e32 v8, 0x50, v8
	v_mul_u32_u24_e32 v9, 0x48, v12
	v_add3_u32 v14, s14, v114, v8
	v_lshlrev_b32_e32 v115, 1, v9
	ds_read_b128 v[8:11], v14
	s_add_i32 s13, 0, 0x1ec00
	v_mul_u32_u24_e32 v17, 40, v12
	v_add3_u32 v16, s13, v13, v114
	s_add_i32 s13, 0, 0x23c00
	v_lshlrev_b32_e32 v24, 1, v17
	v_add3_u32 v20, s13, v24, v114
	ds_read_b128 v[12:15], v14 offset:1280
	ds_read_b128 v[16:19], v16
	ds_read_b128 v[20:23], v20
	s_add_i32 s13, 0, 0x25000
	v_add3_u32 v29, s79, v115, v114
	v_add3_u32 v24, s13, v24, v114
	ds_read_b128 v[24:27], v24
	s_waitcnt lgkmcnt(2)
	v_mfma_f32_16x16x32_bf16 v[0:3], v[8:11], v[16:19], v[0:3]
	ds_read_b128 v[8:11], v29
	v_add3_u32 v32, s85, v28, v114
	ds_read_b128 v[28:31], v29 offset:64
	v_mfma_f32_16x16x32_bf16 v[4:7], v[12:15], v[16:19], v[4:7]
	ds_read_b128 v[12:15], v32
	ds_read_b128 v[32:35], v32 offset:64
	v_add3_u32 v114, s82, v115, v114
	s_and_b32 s7, s7, -16
	s_waitcnt lgkmcnt(1)
	v_mfma_f32_16x16x32_bf16 v[8:11], v[8:11], v[12:15], 0
	s_lshl_b32 s7, s7, 2
	s_add_i32 s7, s7, 0
	s_waitcnt lgkmcnt(0)
	v_mfma_f32_16x16x32_bf16 v[8:11], v[28:31], v[32:35], v[8:11]
	ds_read_b128 v[28:31], v114
	ds_read_b128 v[114:117], v114 offset:64
	v_mfma_f32_16x16x32_bf16 v[8:11], v[20:23], v[16:19], v[8:11]
	s_mul_i32 s7, s7, 36
	v_mul_u32_u24_e32 v20, 0x90, v39
	v_lshl_add_u32 v21, v118, 4, s7
	s_lshl_b32 s7, s12, 6
	s_waitcnt lgkmcnt(1)
	v_mfma_f32_16x16x32_bf16 v[12:15], v[28:31], v[12:15], 0
	v_add3_u32 v20, v20, v21, s7
	s_nop 1
	v_mul_f32_e32 v8, 0x3e800000, v8
	v_mul_f32_e32 v9, 0x3e800000, v9
	v_mul_f32_e32 v10, 0x3e800000, v10
	v_mul_f32_e32 v11, 0x3e800000, v11
	ds_write_b128 v20, v[8:11] offset:49152
	s_waitcnt lgkmcnt(0)
	v_mfma_f32_16x16x32_bf16 v[8:11], v[114:117], v[32:35], v[12:15]
	s_barrier
	s_nop 1
	v_mov_b32_e32 v12, v200
	v_mfma_f32_16x16x32_bf16 v[8:11], v[24:27], v[16:19], v[8:11]
	s_nop 0
	v_readfirstlane_b32 s7, v12
	s_ashr_i32 s7, s7, 6
	s_cmp_gt_i32 s7, 3
	s_cbranch_scc1 .LBB0_488
	v_bfe_u32 v13, v12, 2, 4
	v_and_b32_e32 v14, 3, v12
	v_lshl_or_b32 v13, s7, 4, v13
	v_cmp_eq_u32_e32 vcc, 0, v14
	v_cmp_eq_u32_e64 s[14:15], 1, v14
	v_cmp_eq_u32_e64 s[12:13], 2, v14
	v_cmp_eq_u32_e64 s[16:17], 3, v14
	v_mul_u32_u24_e32 v12, 0x90, v13
	s_movk_i32 s7, 0x410
	v_mov_b32_e32 v15, s84
	v_mul_lo_u32 v28, v13, s83
	v_mad_u32_u24 v15, v14, s7, v15
	v_lshl_add_u32 v28, v14, 1, v28
	ds_read_b128 v[162:165], v12 offset:49152
	ds_read_b128 v[166:169], v12 offset:49168
	ds_read_b128 v[170:173], v12 offset:49184
	ds_read_b128 v[174:177], v12 offset:49200
	ds_read_b128 v[178:181], v12 offset:49216
	ds_read_b128 v[182:185], v12 offset:49232
	ds_read_b128 v[186:189], v12 offset:49248
	ds_read_b128 v[190:193], v12 offset:49264
	ds_read_b32 v122, v15 offset:32
	ds_read_b32 v130, v15 offset:64
	ds_read_b32 v138, v15 offset:96
	ds_read_b32 v146, v15 offset:128
	ds_read_b64 v[154:155], v15 offset:160
	s_waitcnt lgkmcnt(12)
	v_mul_f32_e32 v162, 4.0, v162
	v_cndmask_b32_e32 v16, 0, v162, vcc
	ds_read_b64 v[114:115], v15 offset:192
	s_waitcnt lgkmcnt(5)
	v_fmac_f32_e32 v163, v16, v122
	ds_read_b64 v[122:123], v15 offset:224
	s_nop 0
	v_add_f32_dpp v163, v163, v163 quad_perm:[1,0,3,2] row_mask:0xf bank_mask:0xf bound_ctrl:1
	s_waitcnt lgkmcnt(4)
	s_nop 0
	v_add_f32_dpp v163, v163, v163 quad_perm:[2,3,0,1] row_mask:0xf bank_mask:0xf bound_ctrl:1
	v_cndmask_b32_e64 v16, v16, v163, s[14:15]
	v_fmac_f32_e32 v164, v16, v130
	ds_read_b64 v[130:131], v15 offset:256
	s_nop 0
	v_add_f32_dpp v164, v164, v164 quad_perm:[1,0,3,2] row_mask:0xf bank_mask:0xf bound_ctrl:1
	s_nop 1
	v_add_f32_dpp v164, v164, v164 quad_perm:[2,3,0,1] row_mask:0xf bank_mask:0xf bound_ctrl:1
	v_cndmask_b32_e64 v16, v16, v164, s[12:13]
	v_fmac_f32_e32 v165, v16, v138
	ds_read_b128 v[138:141], v15 offset:288
	s_nop 0
	v_add_f32_dpp v165, v165, v165 quad_perm:[1,0,3,2] row_mask:0xf bank_mask:0xf bound_ctrl:1
	s_waitcnt lgkmcnt(4)
	s_nop 0
	v_add_f32_dpp v165, v165, v165 quad_perm:[2,3,0,1] row_mask:0xf bank_mask:0xf bound_ctrl:1
	v_cndmask_b32_e64 v16, v16, v165, s[16:17]
	v_fmac_f32_e32 v166, v16, v146
	ds_read_b128 v[146:149], v15 offset:320
	s_nop 0
	v_add_f32_dpp v166, v166, v166 quad_perm:[1,0,3,2] row_mask:0xf bank_mask:0xf bound_ctrl:1
	v_fmac_f32_e32 v167, v16, v154
	s_nop 0
	v_add_f32_dpp v166, v166, v166 quad_perm:[2,3,0,1] row_mask:0xf bank_mask:0xf bound_ctrl:1
	v_cndmask_b32_e32 v17, 0, v166, vcc
	v_fmac_f32_e32 v167, v17, v155
	ds_read_b128 v[154:157], v15 offset:352
	s_nop 0
	v_add_f32_dpp v167, v167, v167 quad_perm:[1,0,3,2] row_mask:0xf bank_mask:0xf bound_ctrl:1
	s_waitcnt lgkmcnt(4)
	s_nop 0
	v_add_f32_dpp v167, v167, v167 quad_perm:[2,3,0,1] row_mask:0xf bank_mask:0xf bound_ctrl:1
	v_fmac_f32_e32 v168, v16, v114
	v_cndmask_b32_e64 v17, v17, v167, s[14:15]
	v_fmac_f32_e32 v168, v17, v115
	ds_read_b128 v[114:117], v15 offset:384
	s_nop 0
	v_add_f32_dpp v168, v168, v168 quad_perm:[1,0,3,2] row_mask:0xf bank_mask:0xf bound_ctrl:1
	v_fmac_f32_e32 v169, v16, v122
	s_nop 0
	v_add_f32_dpp v168, v168, v168 quad_perm:[2,3,0,1] row_mask:0xf bank_mask:0xf bound_ctrl:1
	v_cndmask_b32_e64 v17, v17, v168, s[12:13]
	v_fmac_f32_e32 v169, v17, v123
	ds_read_b128 v[122:125], v15 offset:416
	s_nop 0
	v_add_f32_dpp v169, v169, v169 quad_perm:[1,0,3,2] row_mask:0xf bank_mask:0xf bound_ctrl:1
	s_waitcnt lgkmcnt(4)
; #define LAS __attribute__((address_space(3)))
; template <int CTRL> __device__ __forceinline__ float dppf(float x) { return __builtin_bit_cast(float, __builtin_amdgcn_mov_dpp(__builtin_bit_cast(int, x), CTRL, 0xf, 0xf, true)); }
; __device__ __forceinline__ void rwkv_chain(LAS unsigned char* lds, int cid, const bf16_t* P0, const float* mu, const float* w0, const float* w2, const float* a0, const float* a2, ...
;     ...
;             for (int t = 0; t < 32; ++t) { float q0 = (p == 0) ? WS[t * 64 + v] : 0.f, q1 = 0.f;
; #pragma unroll
;                 for (int j4 = 0; j4 < ((t + 3) / 4 + 3) / 4; ++j4) { const f32x4 nv = *(const LAS f32x4*)(NTp + t * 12 + j4 * 4);
;                     q0 += u[j4 * 4] * nv[0]; q1 += u[j4 * 4 + 1] * nv[1]; q0 += u[j4 * 4 + 2] * nv[2]; q1 += u[j4 * 4 + 3] * nv[3]; }
;                 float q = q0 + q1; q += dppf<0xB1>(q); q += dppf<0x4E>(q);
;                 u[t >> 2] = ((t & 3) == p) ? q : u[t >> 2]; asm volatile("" ::: "memory"); }
	s_nop 0
	v_add_f32_dpp v169, v169, v169 quad_perm:[2,3,0,1] row_mask:0xf bank_mask:0xf bound_ctrl:1
	v_fmac_f32_e32 v170, v16, v130
	v_cndmask_b32_e64 v17, v17, v169, s[16:17]
	v_fmac_f32_e32 v170, v17, v131
	ds_read_b128 v[130:133], v15 offset:448
	s_nop 0
	v_add_f32_dpp v170, v170, v170 quad_perm:[1,0,3,2] row_mask:0xf bank_mask:0xf bound_ctrl:1
	v_fmac_f32_e32 v171, v16, v138
	s_nop 0
	v_add_f32_dpp v170, v170, v170 quad_perm:[2,3,0,1] row_mask:0xf bank_mask:0xf bound_ctrl:1
	v_fmac_f32_e32 v171, v17, v139
	v_cndmask_b32_e32 v18, 0, v170, vcc
	v_fmac_f32_e32 v171, v18, v140
	ds_read_b128 v[138:141], v15 offset:480
	s_waitcnt lgkmcnt(4)
	v_add_f32_dpp v171, v171, v171 quad_perm:[1,0,3,2] row_mask:0xf bank_mask:0xf bound_ctrl:1
	v_fmac_f32_e32 v172, v16, v146
	s_nop 0
	v_add_f32_dpp v171, v171, v171 quad_perm:[2,3,0,1] row_mask:0xf bank_mask:0xf bound_ctrl:1
	v_fmac_f32_e32 v172, v17, v147
	v_cndmask_b32_e64 v18, v18, v171, s[14:15]
	v_fmac_f32_e32 v172, v18, v148
	ds_read_b128 v[146:149], v15 offset:512
	s_nop 0
	v_add_f32_dpp v172, v172, v172 quad_perm:[1,0,3,2] row_mask:0xf bank_mask:0xf bound_ctrl:1
	v_fmac_f32_e32 v173, v16, v154
	s_nop 0
	v_add_f32_dpp v172, v172, v172 quad_perm:[2,3,0,1] row_mask:0xf bank_mask:0xf bound_ctrl:1
	v_fmac_f32_e32 v173, v17, v155
	v_cndmask_b32_e64 v18, v18, v172, s[12:13]
	v_fmac_f32_e32 v173, v18, v156
	ds_read_b128 v[154:157], v15 offset:544
	ds_read_b32 v158, v15 offset:560
	v_add_f32_dpp v173, v173, v173 quad_perm:[1,0,3,2] row_mask:0xf bank_mask:0xf bound_ctrl:1
	s_waitcnt lgkmcnt(5)
	v_fmac_f32_e32 v174, v16, v114
	v_add_f32_dpp v173, v173, v173 quad_perm:[2,3,0,1] row_mask:0xf bank_mask:0xf bound_ctrl:1
	v_fmac_f32_e32 v174, v17, v115
	v_cndmask_b32_e64 v18, v18, v173, s[16:17]
	v_fmac_f32_e32 v174, v18, v116
	ds_read_b128 v[114:117], v15 offset:576
	ds_read_b32 v118, v15 offset:592
	v_add_f32_dpp v174, v174, v174 quad_perm:[1,0,3,2] row_mask:0xf bank_mask:0xf bound_ctrl:1
	v_fmac_f32_e32 v175, v16, v122
	v_fmac_f32_e32 v175, v17, v123
	v_add_f32_dpp v174, v174, v174 quad_perm:[2,3,0,1] row_mask:0xf bank_mask:0xf bound_ctrl:1
	v_fmac_f32_e32 v175, v18, v124
	v_cndmask_b32_e32 v19, 0, v174, vcc
	v_fmac_f32_e32 v175, v19, v125
	ds_read_b128 v[122:125], v15 offset:608
	ds_read_b32 v126, v15 offset:624
	v_add_f32_dpp v175, v175, v175 quad_perm:[1,0,3,2] row_mask:0xf bank_mask:0xf bound_ctrl:1
	s_waitcnt lgkmcnt(7)
	v_fmac_f32_e32 v176, v16, v130
	v_add_f32_dpp v175, v175, v175 quad_perm:[2,3,0,1] row_mask:0xf bank_mask:0xf bound_ctrl:1
	v_fmac_f32_e32 v176, v17, v131
	v_fmac_f32_e32 v176, v18, v132
	v_cndmask_b32_e64 v19, v19, v175, s[14:15]
	v_fmac_f32_e32 v176, v19, v133
	ds_read_b128 v[130:133], v15 offset:640
	ds_read_b32 v134, v15 offset:656
	v_add_f32_dpp v176, v176, v176 quad_perm:[1,0,3,2] row_mask:0xf bank_mask:0xf bound_ctrl:1
	v_fmac_f32_e32 v177, v16, v138
	v_fmac_f32_e32 v177, v17, v139
	v_add_f32_dpp v176, v176, v176 quad_perm:[2,3,0,1] row_mask:0xf bank_mask:0xf bound_ctrl:1
	v_fmac_f32_e32 v177, v18, v140
	v_cndmask_b32_e64 v19, v19, v176, s[12:13]
	v_fmac_f32_e32 v177, v19, v141
	ds_read_b128 v[138:141], v15 offset:672
	ds_read_b64 v[142:143], v15 offset:688
	v_add_f32_dpp v177, v177, v177 quad_perm:[1,0,3,2] row_mask:0xf bank_mask:0xf bound_ctrl:1
	s_waitcnt lgkmcnt(8)
	v_fmac_f32_e32 v178, v16, v146
	v_add_f32_dpp v177, v177, v177 quad_perm:[2,3,0,1] row_mask:0xf bank_mask:0xf bound_ctrl:1
	v_fmac_f32_e32 v178, v17, v147
	v_fmac_f32_e32 v178, v18, v148
	v_cndmask_b32_e64 v19, v19, v177, s[16:17]
	v_fmac_f32_e32 v178, v19, v149
	ds_read_b128 v[146:149], v15 offset:704
	ds_read_b64 v[150:151], v15 offset:720
	v_add_f32_dpp v178, v178, v178 quad_perm:[1,0,3,2] row_mask:0xf bank_mask:0xf bound_ctrl:1
	v_pk_mul_f32 v[26:27], v[16:17], v[154:155]
	v_pk_fma_f32 v[26:27], v[18:19], v[156:157], v[26:27]
	v_add_f32_dpp v178, v178, v178 quad_perm:[2,3,0,1] row_mask:0xf bank_mask:0xf bound_ctrl:1
	v_add_f32_e32 v26, v26, v27
	v_add_f32_e32 v179, v179, v26
	v_cndmask_b32_e32 v20, 0, v178, vcc
	v_fmac_f32_e32 v179, v20, v158
	ds_read_b128 v[154:157], v15 offset:736
	ds_read_b64 v[158:159], v15 offset:752
	s_waitcnt lgkmcnt(8)
	v_add_f32_dpp v179, v179, v179 quad_perm:[1,0,3,2] row_mask:0xf bank_mask:0xf bound_ctrl:1
	v_pk_mul_f32 v[24:25], v[16:17], v[114:115]
	v_pk_fma_f32 v[24:25], v[18:19], v[116:117], v[24:25]
	v_add_f32_dpp v179, v179, v179 quad_perm:[2,3,0,1] row_mask:0xf bank_mask:0xf bound_ctrl:1
	v_add_f32_e32 v24, v24, v25
	v_add_f32_e32 v180, v180, v24
	v_cndmask_b32_e64 v20, v20, v179, s[14:15]
	v_fmac_f32_e32 v180, v20, v118
	ds_read_b128 v[114:117], v15 offset:768
	ds_read_b64 v[118:119], v15 offset:784
	v_add_f32_dpp v180, v180, v180 quad_perm:[1,0,3,2] row_mask:0xf bank_mask:0xf bound_ctrl:1
	v_pk_mul_f32 v[26:27], v[16:17], v[122:123]
	v_pk_fma_f32 v[26:27], v[18:19], v[124:125], v[26:27]
	v_add_f32_dpp v180, v180, v180 quad_perm:[2,3,0,1] row_mask:0xf bank_mask:0xf bound_ctrl:1
	v_add_f32_e32 v26, v26, v27
	v_add_f32_e32 v181, v181, v26
	v_cndmask_b32_e64 v20, v20, v180, s[12:13]
	v_fmac_f32_e32 v181, v20, v126
	ds_read_b128 v[122:125], v15 offset:800
	ds_read_b128 v[126:129], v15 offset:816
	s_waitcnt lgkmcnt(8)
; #define LAS __attribute__((address_space(3)))
; __device__ __forceinline__ unsigned f2bf(float f) { return pk2(f, 0.f) & 0xffffu; }
; template <int CTRL> __device__ __forceinline__ float dppf(float x) { return __builtin_bit_cast(float, __builtin_amdgcn_mov_dpp(__builtin_bit_cast(int, x), CTRL, 0xf, 0xf, true)); }
; __device__ __forceinline__ void rwkv_chain(LAS unsigned char* lds, int cid, const bf16_t* P0, const float* mu, const float* w0, const float* w2, const float* a0, const float* a2, ...
;     ...
;             for (int t = 0; t < 32; ++t) { float q0 = (p == 0) ? WS[t * 64 + v] : 0.f, q1 = 0.f;
; #pragma unroll
;                 for (int j4 = 0; j4 < ((t + 3) / 4 + 3) / 4; ++j4) { const f32x4 nv = *(const LAS f32x4*)(NTp + t * 12 + j4 * 4);
;                     q0 += u[j4 * 4] * nv[0]; q1 += u[j4 * 4 + 1] * nv[1]; q0 += u[j4 * 4 + 2] * nv[2]; q1 += u[j4 * 4 + 3] * nv[3]; }
;                 float q = q0 + q1; q += dppf<0xB1>(q); q += dppf<0x4E>(q);
;                 u[t >> 2] = ((t & 3) == p) ? q : u[t >> 2]; asm volatile("" ::: "memory"); }
; #pragma unroll
;             for (int j = 0; j < 8; ++j) Ub[v * 40 + 4 * j + p] = (bf16_t)f2bf(u[j]); } }
	v_add_f32_dpp v181, v181, v181 quad_perm:[1,0,3,2] row_mask:0xf bank_mask:0xf bound_ctrl:1
	v_pk_mul_f32 v[24:25], v[16:17], v[130:131]
	v_pk_fma_f32 v[24:25], v[18:19], v[132:133], v[24:25]
	v_add_f32_dpp v181, v181, v181 quad_perm:[2,3,0,1] row_mask:0xf bank_mask:0xf bound_ctrl:1
	v_add_f32_e32 v24, v24, v25
	v_add_f32_e32 v182, v182, v24
	v_cndmask_b32_e64 v20, v20, v181, s[16:17]
	v_fmac_f32_e32 v182, v20, v134
	ds_read_b128 v[130:133], v15 offset:832
	ds_read_b128 v[134:137], v15 offset:848
	v_pk_mul_f32 v[26:27], v[16:17], v[138:139]
	v_add_f32_dpp v182, v182, v182 quad_perm:[1,0,3,2] row_mask:0xf bank_mask:0xf bound_ctrl:1
	v_pk_fma_f32 v[26:27], v[18:19], v[140:141], v[26:27]
	v_fmac_f32_e32 v183, v20, v142
	v_add_f32_dpp v182, v182, v182 quad_perm:[2,3,0,1] row_mask:0xf bank_mask:0xf bound_ctrl:1
	v_add_f32_e32 v26, v26, v27
	v_add_f32_e32 v183, v183, v26
	v_cndmask_b32_e32 v21, 0, v182, vcc
	v_fmac_f32_e32 v183, v21, v143
	ds_read_b128 v[138:141], v15 offset:864
	ds_read_b128 v[142:145], v15 offset:880
	s_waitcnt lgkmcnt(8)
	v_add_f32_dpp v183, v183, v183 quad_perm:[1,0,3,2] row_mask:0xf bank_mask:0xf bound_ctrl:1
	v_pk_mul_f32 v[24:25], v[16:17], v[146:147]
	v_pk_fma_f32 v[24:25], v[18:19], v[148:149], v[24:25]
	v_fmac_f32_e32 v184, v20, v150
	v_add_f32_dpp v183, v183, v183 quad_perm:[2,3,0,1] row_mask:0xf bank_mask:0xf bound_ctrl:1
	v_add_f32_e32 v24, v24, v25
	v_add_f32_e32 v184, v184, v24
	v_cndmask_b32_e64 v21, v21, v183, s[14:15]
	v_fmac_f32_e32 v184, v21, v151
	ds_read_b128 v[146:149], v15 offset:896
	ds_read_b128 v[150:153], v15 offset:912
	v_pk_mul_f32 v[26:27], v[16:17], v[154:155]
	v_add_f32_dpp v184, v184, v184 quad_perm:[1,0,3,2] row_mask:0xf bank_mask:0xf bound_ctrl:1
	v_pk_fma_f32 v[26:27], v[18:19], v[156:157], v[26:27]
	v_fmac_f32_e32 v185, v20, v158
	v_add_f32_dpp v184, v184, v184 quad_perm:[2,3,0,1] row_mask:0xf bank_mask:0xf bound_ctrl:1
	v_add_f32_e32 v26, v26, v27
	v_add_f32_e32 v185, v185, v26
	v_cndmask_b32_e64 v21, v21, v184, s[12:13]
	v_fmac_f32_e32 v185, v21, v159
	ds_read_b128 v[154:157], v15 offset:928
	ds_read_b128 v[158:161], v15 offset:944
	s_waitcnt lgkmcnt(8)
	v_add_f32_dpp v185, v185, v185 quad_perm:[1,0,3,2] row_mask:0xf bank_mask:0xf bound_ctrl:1
	v_pk_mul_f32 v[24:25], v[16:17], v[114:115]
	v_pk_fma_f32 v[24:25], v[18:19], v[116:117], v[24:25]
	v_fmac_f32_e32 v186, v20, v118
	v_add_f32_dpp v185, v185, v185 quad_perm:[2,3,0,1] row_mask:0xf bank_mask:0xf bound_ctrl:1
	v_add_f32_e32 v24, v24, v25
	v_add_f32_e32 v186, v186, v24
	v_cndmask_b32_e64 v21, v21, v185, s[16:17]
	v_fmac_f32_e32 v186, v21, v119
	ds_read_b128 v[114:117], v15 offset:960
	ds_read_b128 v[118:121], v15 offset:976
	v_pk_mul_f32 v[26:27], v[16:17], v[122:123]
	v_add_f32_dpp v186, v186, v186 quad_perm:[1,0,3,2] row_mask:0xf bank_mask:0xf bound_ctrl:1
	v_pk_fma_f32 v[26:27], v[18:19], v[124:125], v[26:27]
	v_pk_fma_f32 v[26:27], v[20:21], v[126:127], v[26:27]
	v_add_f32_dpp v186, v186, v186 quad_perm:[2,3,0,1] row_mask:0xf bank_mask:0xf bound_ctrl:1
	v_add_f32_e32 v26, v26, v27
	v_add_f32_e32 v187, v187, v26
	v_cndmask_b32_e32 v22, 0, v186, vcc
	v_fmac_f32_e32 v187, v22, v128
	ds_read_b128 v[122:125], v15 offset:992
	ds_read_b128 v[126:129], v15 offset:1008
	s_waitcnt lgkmcnt(8)
	v_add_f32_dpp v187, v187, v187 quad_perm:[1,0,3,2] row_mask:0xf bank_mask:0xf bound_ctrl:1
	v_pk_mul_f32 v[24:25], v[16:17], v[130:131]
	v_pk_fma_f32 v[24:25], v[18:19], v[132:133], v[24:25]
	v_pk_fma_f32 v[24:25], v[20:21], v[134:135], v[24:25]
	v_add_f32_dpp v187, v187, v187 quad_perm:[2,3,0,1] row_mask:0xf bank_mask:0xf bound_ctrl:1
	v_add_f32_e32 v24, v24, v25
	v_add_f32_e32 v188, v188, v24
	v_cndmask_b32_e64 v22, v22, v187, s[14:15]
	v_fmac_f32_e32 v188, v22, v136
	v_pk_mul_f32 v[26:27], v[16:17], v[138:139]
	v_pk_fma_f32 v[26:27], v[18:19], v[140:141], v[26:27]
	v_add_f32_dpp v188, v188, v188 quad_perm:[1,0,3,2] row_mask:0xf bank_mask:0xf bound_ctrl:1
	v_pk_fma_f32 v[26:27], v[20:21], v[142:143], v[26:27]
	v_add_f32_e32 v26, v26, v27
	v_add_f32_dpp v188, v188, v188 quad_perm:[2,3,0,1] row_mask:0xf bank_mask:0xf bound_ctrl:1
	v_add_f32_e32 v189, v189, v26
	v_cndmask_b32_e64 v22, v22, v188, s[12:13]
	v_fmac_f32_e32 v189, v22, v144
	s_waitcnt lgkmcnt(4)
	v_pk_mul_f32 v[24:25], v[16:17], v[146:147]
	v_add_f32_dpp v189, v189, v189 quad_perm:[1,0,3,2] row_mask:0xf bank_mask:0xf bound_ctrl:1
	v_pk_fma_f32 v[24:25], v[18:19], v[148:149], v[24:25]
	v_pk_fma_f32 v[24:25], v[20:21], v[150:151], v[24:25]
	v_add_f32_dpp v189, v189, v189 quad_perm:[2,3,0,1] row_mask:0xf bank_mask:0xf bound_ctrl:1
	v_add_f32_e32 v24, v24, v25
	v_add_f32_e32 v190, v190, v24
	v_cndmask_b32_e64 v22, v22, v189, s[16:17]
	v_fmac_f32_e32 v190, v22, v152
	v_pk_mul_f32 v[26:27], v[16:17], v[154:155]
	v_pk_fma_f32 v[26:27], v[18:19], v[156:157], v[26:27]
	v_add_f32_dpp v190, v190, v190 quad_perm:[1,0,3,2] row_mask:0xf bank_mask:0xf bound_ctrl:1
	v_pk_fma_f32 v[26:27], v[20:21], v[158:159], v[26:27]
	v_fmac_f32_e32 v191, v22, v160
	v_add_f32_dpp v190, v190, v190 quad_perm:[2,3,0,1] row_mask:0xf bank_mask:0xf bound_ctrl:1
	v_add_f32_e32 v26, v26, v27
	v_add_f32_e32 v191, v191, v26
	v_cndmask_b32_e32 v23, 0, v190, vcc
	v_fmac_f32_e32 v191, v23, v161
	s_waitcnt lgkmcnt(0)
	v_pk_mul_f32 v[24:25], v[16:17], v[114:115]
	v_pk_fma_f32 v[24:25], v[18:19], v[116:117], v[24:25]
	v_add_f32_dpp v191, v191, v191 quad_perm:[1,0,3,2] row_mask:0xf bank_mask:0xf bound_ctrl:1
	v_pk_fma_f32 v[24:25], v[20:21], v[118:119], v[24:25]
	v_fmac_f32_e32 v192, v22, v120
	v_add_f32_dpp v191, v191, v191 quad_perm:[2,3,0,1] row_mask:0xf bank_mask:0xf bound_ctrl:1
	v_add_f32_e32 v24, v24, v25
	v_add_f32_e32 v192, v192, v24
	v_cndmask_b32_e64 v23, v23, v191, s[14:15]
	v_fmac_f32_e32 v192, v23, v121
	v_pk_mul_f32 v[26:27], v[16:17], v[122:123]
	v_pk_fma_f32 v[26:27], v[18:19], v[124:125], v[26:27]
	v_add_f32_dpp v192, v192, v192 quad_perm:[1,0,3,2] row_mask:0xf bank_mask:0xf bound_ctrl:1
	v_pk_fma_f32 v[26:27], v[20:21], v[126:127], v[26:27]
	v_fmac_f32_e32 v193, v22, v128
	v_add_f32_dpp v192, v192, v192 quad_perm:[2,3,0,1] row_mask:0xf bank_mask:0xf bound_ctrl:1
	v_add_f32_e32 v26, v26, v27
	v_add_f32_e32 v193, v193, v26
	v_cndmask_b32_e64 v23, v23, v192, s[12:13]
	v_fmac_f32_e32 v193, v23, v129
	s_nop 1
	v_add_f32_dpp v193, v193, v193 quad_perm:[1,0,3,2] row_mask:0xf bank_mask:0xf bound_ctrl:1
	s_nop 1
	v_add_f32_dpp v193, v193, v193 quad_perm:[2,3,0,1] row_mask:0xf bank_mask:0xf bound_ctrl:1
	v_cndmask_b32_e64 v23, v23, v193, s[16:17]
	v_cvt_pk_bf16_f32 v30, v16, v16
	ds_write_b16 v28, v30 offset:58368
	v_cvt_pk_bf16_f32 v31, v17, v17
	ds_write_b16 v28, v31 offset:58376
	v_cvt_pk_bf16_f32 v30, v18, v18
	ds_write_b16 v28, v30 offset:58384
	v_cvt_pk_bf16_f32 v31, v19, v19
	ds_write_b16 v28, v31 offset:58392
	v_cvt_pk_bf16_f32 v30, v20, v20
	ds_write_b16 v28, v30 offset:58400
	v_cvt_pk_bf16_f32 v31, v21, v21
	ds_write_b16 v28, v31 offset:58408
	v_cvt_pk_bf16_f32 v30, v22, v22
	ds_write_b16 v28, v30 offset:58416
	v_cvt_pk_bf16_f32 v31, v23, v23
	ds_write_b16 v28, v31 offset:58424
	s_branch .LBB0_488
